# dense attention: pair-units dealt XCD-locally (each XCD's 14 attention blocks share two (batch, kv-head) groups, K/V stay in that L2)
# baseline (speedup 1.0000x reference)
.Lga_entry:
	s_mov_b64 exec, -1
	s_load_dwordx2 s[4:5], s[64:65], 0xf8
	s_mov_b32 s100, 0x3e38aa3b
	s_mov_b32 s101, 0
	v_mov_b32_e32 v86, 0x3e38aa3b
	v_and_b32_e32 v144, 63, v247
	v_lshrrev_b32_e32 v145, 6, v247
	v_and_b32_e32 v146, 15, v144
	v_lshrrev_b32_e32 v147, 4, v144
	v_readfirstlane_b32 s21, v145
	v_bfe_u32 v148, v146, 1, 3
	v_lshlrev_b32_e32 v149, 7, v146
	v_xor_b32_e32 v150, v147, v148
	v_lshl_add_u32 v136, v150, 4, v149
	v_add_u32_e32 v136, 16, v136
	v_xor_b32_e32 v150, 4, v150
	v_lshl_add_u32 v137, v150, 4, v149
	v_add_u32_e32 v137, 16, v137
	v_lshrrev_b32_e32 v151, 1, v147
	v_and_b32_e32 v152, 1, v147
	v_lshlrev_b32_e32 v152, 3, v152
	v_add_u32_e32 v152, v152, v149
	v_add_u32_e32 v152, 0x2010, v152
	v_add_u32_e32 v153, 0, v151
	v_xor_b32_e32 v153, v153, v148
	v_lshl_add_u32 v138, v153, 4, v152
	v_add_u32_e32 v153, 2, v151
	v_xor_b32_e32 v153, v153, v148
	v_lshl_add_u32 v139, v153, 4, v152
	v_add_u32_e32 v153, 4, v151
	v_xor_b32_e32 v153, v153, v148
	v_lshl_add_u32 v140, v153, 4, v152
	v_add_u32_e32 v153, 6, v151
	v_xor_b32_e32 v153, v153, v148
	v_lshl_add_u32 v141, v153, 4, v152
	s_lshl_b32 s0, s21, 3
	v_lshrrev_b32_e32 v153, 3, v144
	v_add_u32_e32 v153, s0, v153
	v_bfe_u32 v154, v153, 1, 3
	v_and_b32_e32 v155, 7, v144
	v_xor_b32_e32 v154, v154, v155
	v_lshlrev_b32_e32 v154, 4, v154
	v_mul_u32_u24_e32 v142, 0x3000, v153
	v_add_u32_e32 v142, v142, v154
	v_mul_u32_u24_e32 v143, 0x9000, v153
	v_add_u32_e32 v143, v143, v154
	s_lshl_b32 s32, s21, 10
	s_add_u32 s32, s32, 16
	s_add_u32 s41, s32, 0x2000
	s_and_b32 s1, s40, 7
	s_lshl_b32 s1, s1, 5
	s_sub_u32 s33, s40, 144
	s_lshr_b32 s33, s33, 3
	s_add_u32 s1, s1, s33
	s_and_b32 s34, s1, 0xffffffe0
	s_add_u32 s34, s34, 28
	s_waitcnt lgkmcnt(0)

.Lga_nostore:
	s_bitcmp1_b32 s101, 1
	s_cbranch_scc1 .Lga_done
	s_add_u32 s1, s1, 14
	s_cmp_lt_u32 s1, s34
	s_cbranch_scc1 .Lga_unit
	s_cmp_lt_u32 s33, 8
	s_cbranch_scc0 .Lga_done
	s_lshr_b32 s1, s33, 1
	s_add_u32 s1, s1, s34
	s_and_b32 s0, s33, 1
	s_lshr_b32 s92, s21, 2
	s_cmp_lg_u32 s92, s0
	s_cselect_b32 s101, 3, 2
	s_branch .Lga_unit
